# first-barrier census: 16 per-XCD counter loads in flight with one wait instead of 16 serialized round trips
# speedup vs baseline: 1.0014x; 1.0014x over previous
; DEV unsigned xb_ld(unsigned* p)              { return __hip_atomic_load(p, __ATOMIC_RELAXED, __HIP_MEMORY_SCOPE_AGENT); }
; DEV void xcd_barrier_complete(unsigned* bar, unsigned x, unsigned& nloc, unsigned& nx) {
;   const unsigned G = gridDim.x * gridDim.y * gridDim.z;
;   unsigned sum, cnt, mine, sp = 0u;
;   for (;;) {
;     sum = 0u; cnt = 0u; mine = 0u;
; #pragma unroll
;     for (unsigned j = 0; j < 16; ++j) { const unsigned c = xb_ld(&bar[XB_XCNT(j)]); sum += c; cnt += (c > 0u) ? 1u : 0u; mine = (j == x) ? c : mine; }
;     if (sum == G) break;
;     __builtin_amdgcn_s_sleep(1);
;     if ((++sp & 255u) == 0u) { if (xb_ld(&bar[XB_TMO])) break; if (sp > XB_SPIN_CAP) { atomicAdd(&bar[XB_TMO], 1u); break; } }
;   }
;   nloc = mine > 0u ? mine : 1u; nx = cnt > 0u ? cnt : 1u;
; }
.LBB0_15:
	v_readlane_b32 s2, v250, 25
	v_readlane_b32 s3, v250, 26
	v_readlane_b32 s4, v250, 22
	s_waitcnt lgkmcnt(0)
	s_nop 4
	global_load_dword v0, v169, s[2:3] sc1
	global_load_dword v1, v169, s[2:3] offset:256 sc1
	global_load_dword v2, v169, s[2:3] offset:512 sc1
	global_load_dword v3, v169, s[2:3] offset:768 sc1
	global_load_dword v4, v169, s[2:3] offset:1024 sc1
	global_load_dword v5, v169, s[2:3] offset:1280 sc1
	global_load_dword v6, v169, s[2:3] offset:1536 sc1
	global_load_dword v7, v169, s[2:3] offset:1792 sc1
	global_load_dword v8, v169, s[2:3] offset:2048 sc1
	global_load_dword v9, v169, s[2:3] offset:2304 sc1
	global_load_dword v10, v169, s[2:3] offset:2560 sc1
	global_load_dword v11, v169, s[2:3] offset:2816 sc1
	global_load_dword v12, v169, s[2:3] offset:3072 sc1
	global_load_dword v13, v169, s[2:3] offset:3328 sc1
	global_load_dword v14, v169, s[2:3] offset:3584 sc1
	global_load_dword v15, v169, s[2:3] offset:3840 sc1
	s_waitcnt vmcnt(0)
	v_add_u32_e32 v16, v1, v0
	v_add_u32_e32 v16, v16, v2
	v_add_u32_e32 v16, v16, v3
	v_add_u32_e32 v16, v16, v4
	v_add_u32_e32 v16, v16, v5
	v_add_u32_e32 v16, v16, v6
	v_add_u32_e32 v16, v16, v7
	v_add_u32_e32 v16, v16, v8
	v_add_u32_e32 v16, v16, v9
	v_add_u32_e32 v16, v16, v10
	v_add_u32_e32 v16, v16, v11
	v_add_u32_e32 v16, v16, v12
	v_add_u32_e32 v16, v16, v13
	v_add_u32_e32 v16, v16, v14
	v_add_u32_e32 v16, v16, v15
	s_mov_b64 s[2:3], -1
	v_cmp_eq_u32_e32 vcc, s4, v16
	s_mov_b64 s[4:5], -1
	s_cbranch_vccnz .LBB0_14
	s_and_b32 s2, s6, 0xff
	s_cmp_eq_u32 s2, 0
	s_mov_b64 s[2:3], -1
	s_mov_b64 s[8:9], -1
	s_sleep 1
	s_cbranch_scc1 .LBB0_19
	s_and_b64 vcc, exec, s[8:9]
	s_cbranch_vccz .LBB0_14
